# P4->P5 XCC-local barrier: leader releases the local workgroups first, then writes the L2 back and bumps the knorm-done counter
# speedup vs baseline: 1.0027x; 1.0027x over previous
.LBB0_634:
	s_andn2_saveexec_b64 s[2:3], s[8:9]
	s_cbranch_execz .LBB0_654
	s_mov_b64 s[8:9], exec
	s_mov_b32 s99, 0
	s_cmp_lg_u32 s98, 0
	s_cbranch_scc0 .Lxl_full_5
	s_mov_b64 s[8:9], exec
	s_mov_b32 s99, 0x5a
	buffer_inv sc1
	s_branch .LBB0_651

.LBB0_653:
	s_or_b64 exec, exec, s[10:11]
	s_waitcnt vmcnt(0)
	s_cmp_eq_u32 s99, 0x5a
	s_cbranch_scc0 .Lb5_nowb
	buffer_wbl2 sc1
	s_waitcnt vmcnt(0)
	v_mov_b32_e32 v14, 0xfa03a00
	v_mov_b32_e32 v15, 1
	global_atomic_add v14, v15, s[74:75]
.Lb5_nowb:
.LBB0_654:
	s_or_b64 exec, exec, s[0:1]
